# SwiGLU epilogue rewritten with packed f32 VALU ops (v_pk_mul_f32, v_pk_add_f32), same per-element IEEE operations
# speedup vs baseline: 1.0377x; 1.0022x over previous
; __device__ __forceinline__ v4u pk8(f32x4 a, f32x4 b) { v4u w; w.x = pk2(a[0], a[1]); w.y = pk2(a[2], a[3]); w.z = pk2(b[0], b[1]); w.w = pk2(b[2], b[3]); return w; }
;     __device__ __forceinline__ void operator()(const accv (&acc)[2][2][4][2], const pg8::Unit& u, int wr, int wc, int fr, int fq) const {
;         const int row0 = u.pm * 256 + wr * 64 + fr, col0 = u.pn * 128 + wc * 32 + 8 * fq;
; #pragma unroll
;         for (int ai = 0; ai < 2; ++ai)
; #pragma unroll
;             for (int m = 0; m < 4; ++m) {
;                 f32x4 a[2];
; #pragma unroll
;                 for (int n = 0; n < 2; ++n)
; #pragma unroll
;                     for (int i = 0; i < 4; ++i) { const float g = acc[ai][0][m][n][i], up = acc[ai][1][m][n][i];
;                         a[n][i] = g * __builtin_amdgcn_rcpf(1.f + __builtin_amdgcn_exp2f(-1.4426950408889634f * g)) * up; }
;                 *(v4u*)(O + (unsigned)((row0 + ai * 128 + m * 16) * FF + col0)) = pk8(a[0], a[1]);
;             }
;     }
.LBB0_233:
	v_lshl_add_u32 v147, s78, 8, v140
	v_lshl_or_b32 v146, s14, 7, v142
	s_movk_i32 s12, 0x1600
	s_andn2_b64 vcc, exec, s[4:5]
	s_mov_b64 s[4:5], -1
	s_mov_b32 s100, 0xbfb8aa3b
	s_mov_b32 s101, 0xbfb8aa3b
	v_mad_u64_u32 v[152:153], s[14:15], v147, s12, v[146:147]
	v_pk_mul_f32 v[144:145], v[124:125], s[100:101] op_sel_hi:[1,0]
	v_pk_mul_f32 v[146:147], v[126:127], s[100:101] op_sel_hi:[1,0]
	v_pk_mul_f32 v[148:149], v[120:121], s[100:101] op_sel_hi:[1,0]
	v_pk_mul_f32 v[150:151], v[122:123], s[100:101] op_sel_hi:[1,0]
	v_exp_f32_e32 v144, v144
	v_exp_f32_e32 v145, v145
	v_exp_f32_e32 v146, v146
	v_exp_f32_e32 v147, v147
	v_exp_f32_e32 v148, v148
	v_exp_f32_e32 v149, v149
	v_exp_f32_e32 v150, v150
	v_exp_f32_e32 v151, v151
	v_pk_add_f32 v[144:145], v[144:145], 1.0 op_sel_hi:[1,0]
	v_pk_add_f32 v[146:147], v[146:147], 1.0 op_sel_hi:[1,0]
	v_pk_add_f32 v[148:149], v[148:149], 1.0 op_sel_hi:[1,0]
	v_pk_add_f32 v[150:151], v[150:151], 1.0 op_sel_hi:[1,0]
	v_rcp_f32_e32 v144, v144
	v_rcp_f32_e32 v145, v145
	v_rcp_f32_e32 v146, v146
	v_rcp_f32_e32 v147, v147
	v_rcp_f32_e32 v148, v148
	v_rcp_f32_e32 v149, v149
	v_rcp_f32_e32 v150, v150
	v_rcp_f32_e32 v151, v151
	v_pk_mul_f32 v[124:125], v[124:125], v[144:145]
	v_pk_mul_f32 v[126:127], v[126:127], v[146:147]
	v_pk_mul_f32 v[120:121], v[120:121], v[148:149]
	v_pk_mul_f32 v[122:123], v[122:123], v[150:151]
	v_mov_b32_e32 v168, v152
	v_pk_mul_f32 v[124:125], v[124:125], v[116:117]
	v_pk_mul_f32 v[126:127], v[126:127], v[118:119]
	v_pk_mul_f32 v[120:121], v[120:121], v[112:113]
	v_pk_mul_f32 v[122:123], v[122:123], v[114:115]
	v_lshl_add_u64 v[154:155], v[168:169], 1, s[64:65]
	v_cvt_pk_bf16_f32 v112, v124, v125
	v_cvt_pk_bf16_f32 v113, v126, v127
	v_cvt_pk_bf16_f32 v114, v120, v121
	v_cvt_pk_bf16_f32 v115, v122, v123
	global_store_dwordx4 v[154:155], v[112:115], off
	v_pk_mul_f32 v[144:145], v[108:109], s[100:101] op_sel_hi:[1,0]
	v_pk_mul_f32 v[146:147], v[110:111], s[100:101] op_sel_hi:[1,0]
	v_pk_mul_f32 v[148:149], v[104:105], s[100:101] op_sel_hi:[1,0]
	v_pk_mul_f32 v[150:151], v[106:107], s[100:101] op_sel_hi:[1,0]
	v_exp_f32_e32 v144, v144
	v_exp_f32_e32 v145, v145
	v_exp_f32_e32 v146, v146
	v_exp_f32_e32 v147, v147
	v_exp_f32_e32 v148, v148
	v_exp_f32_e32 v149, v149
	v_exp_f32_e32 v150, v150
	v_exp_f32_e32 v151, v151
	v_pk_add_f32 v[144:145], v[144:145], 1.0 op_sel_hi:[1,0]
	v_pk_add_f32 v[146:147], v[146:147], 1.0 op_sel_hi:[1,0]
	v_pk_add_f32 v[148:149], v[148:149], 1.0 op_sel_hi:[1,0]
	v_pk_add_f32 v[150:151], v[150:151], 1.0 op_sel_hi:[1,0]
	v_rcp_f32_e32 v144, v144
	v_rcp_f32_e32 v145, v145
	v_rcp_f32_e32 v146, v146
	v_rcp_f32_e32 v147, v147
	v_rcp_f32_e32 v148, v148
	v_rcp_f32_e32 v149, v149
	v_rcp_f32_e32 v150, v150
	v_rcp_f32_e32 v151, v151
	v_pk_mul_f32 v[108:109], v[108:109], v[144:145]
	v_pk_mul_f32 v[110:111], v[110:111], v[146:147]
	v_pk_mul_f32 v[104:105], v[104:105], v[148:149]
	v_pk_mul_f32 v[106:107], v[106:107], v[150:151]
	v_add_u32_e32 v168, 0x16000, v152
	v_pk_mul_f32 v[108:109], v[108:109], v[100:101]
	v_pk_mul_f32 v[110:111], v[110:111], v[102:103]
	v_pk_mul_f32 v[104:105], v[104:105], v[96:97]
	v_pk_mul_f32 v[106:107], v[106:107], v[98:99]
	v_lshl_add_u64 v[154:155], v[168:169], 1, s[64:65]
	v_cvt_pk_bf16_f32 v96, v108, v109
	v_cvt_pk_bf16_f32 v97, v110, v111
	v_cvt_pk_bf16_f32 v98, v104, v105
	v_cvt_pk_bf16_f32 v99, v106, v107
	global_store_dwordx4 v[154:155], v[96:99], off
	v_pk_mul_f32 v[144:145], v[92:93], s[100:101] op_sel_hi:[1,0]
	v_pk_mul_f32 v[146:147], v[94:95], s[100:101] op_sel_hi:[1,0]
	v_pk_mul_f32 v[148:149], v[88:89], s[100:101] op_sel_hi:[1,0]
	v_pk_mul_f32 v[150:151], v[90:91], s[100:101] op_sel_hi:[1,0]
	v_exp_f32_e32 v144, v144
	v_exp_f32_e32 v145, v145
	v_exp_f32_e32 v146, v146
	v_exp_f32_e32 v147, v147
	v_exp_f32_e32 v148, v148
	v_exp_f32_e32 v149, v149
	v_exp_f32_e32 v150, v150
	v_exp_f32_e32 v151, v151
	v_pk_add_f32 v[144:145], v[144:145], 1.0 op_sel_hi:[1,0]
	v_pk_add_f32 v[146:147], v[146:147], 1.0 op_sel_hi:[1,0]
	v_pk_add_f32 v[148:149], v[148:149], 1.0 op_sel_hi:[1,0]
	v_pk_add_f32 v[150:151], v[150:151], 1.0 op_sel_hi:[1,0]
	v_rcp_f32_e32 v144, v144
	v_rcp_f32_e32 v145, v145
	v_rcp_f32_e32 v146, v146
	v_rcp_f32_e32 v147, v147
	v_rcp_f32_e32 v148, v148
	v_rcp_f32_e32 v149, v149
	v_rcp_f32_e32 v150, v150
	v_rcp_f32_e32 v151, v151
	v_pk_mul_f32 v[92:93], v[92:93], v[144:145]
	v_pk_mul_f32 v[94:95], v[94:95], v[146:147]
	v_pk_mul_f32 v[88:89], v[88:89], v[148:149]
	v_pk_mul_f32 v[90:91], v[90:91], v[150:151]
	v_add_u32_e32 v168, 0x2c000, v152
	v_pk_mul_f32 v[92:93], v[92:93], v[84:85]
	v_pk_mul_f32 v[94:95], v[94:95], v[86:87]
	v_pk_mul_f32 v[88:89], v[88:89], v[80:81]
	v_pk_mul_f32 v[90:91], v[90:91], v[82:83]
	v_lshl_add_u64 v[154:155], v[168:169], 1, s[64:65]
	v_cvt_pk_bf16_f32 v80, v92, v93
	v_cvt_pk_bf16_f32 v81, v94, v95
	v_cvt_pk_bf16_f32 v82, v88, v89
	v_cvt_pk_bf16_f32 v83, v90, v91
	global_store_dwordx4 v[154:155], v[80:83], off
	v_pk_mul_f32 v[144:145], v[76:77], s[100:101] op_sel_hi:[1,0]
	v_pk_mul_f32 v[146:147], v[78:79], s[100:101] op_sel_hi:[1,0]
	v_pk_mul_f32 v[148:149], v[72:73], s[100:101] op_sel_hi:[1,0]
	v_pk_mul_f32 v[150:151], v[74:75], s[100:101] op_sel_hi:[1,0]
	v_exp_f32_e32 v144, v144
	v_exp_f32_e32 v145, v145
	v_exp_f32_e32 v146, v146
	v_exp_f32_e32 v147, v147
	v_exp_f32_e32 v148, v148
	v_exp_f32_e32 v149, v149
	v_exp_f32_e32 v150, v150
	v_exp_f32_e32 v151, v151
	v_pk_add_f32 v[144:145], v[144:145], 1.0 op_sel_hi:[1,0]
	v_pk_add_f32 v[146:147], v[146:147], 1.0 op_sel_hi:[1,0]
	v_pk_add_f32 v[148:149], v[148:149], 1.0 op_sel_hi:[1,0]
	v_pk_add_f32 v[150:151], v[150:151], 1.0 op_sel_hi:[1,0]
	v_rcp_f32_e32 v144, v144
; __device__ __forceinline__ v4u pk8(f32x4 a, f32x4 b) { v4u w; w.x = pk2(a[0], a[1]); w.y = pk2(a[2], a[3]); w.z = pk2(b[0], b[1]); w.w = pk2(b[2], b[3]); return w; }
;     __device__ __forceinline__ void operator()(const accv (&acc)[2][2][4][2], const pg8::Unit& u, int wr, int wc, int fr, int fq) const {
;         const int row0 = u.pm * 256 + wr * 64 + fr, col0 = u.pn * 128 + wc * 32 + 8 * fq;
; #pragma unroll
;         for (int ai = 0; ai < 2; ++ai)
; #pragma unroll
;             for (int m = 0; m < 4; ++m) {
;                 f32x4 a[2];
; #pragma unroll
;                 for (int n = 0; n < 2; ++n)
; #pragma unroll
;                     for (int i = 0; i < 4; ++i) { const float g = acc[ai][0][m][n][i], up = acc[ai][1][m][n][i];
;                         a[n][i] = g * __builtin_amdgcn_rcpf(1.f + __builtin_amdgcn_exp2f(-1.4426950408889634f * g)) * up; }
;                 *(v4u*)(O + (unsigned)((row0 + ai * 128 + m * 16) * FF + col0)) = pk8(a[0], a[1]);
;             }
;     }
	v_rcp_f32_e32 v145, v145
	v_rcp_f32_e32 v146, v146
	v_rcp_f32_e32 v147, v147
	v_rcp_f32_e32 v148, v148
	v_rcp_f32_e32 v149, v149
	v_rcp_f32_e32 v150, v150
	v_rcp_f32_e32 v151, v151
	v_pk_mul_f32 v[76:77], v[76:77], v[144:145]
	v_pk_mul_f32 v[78:79], v[78:79], v[146:147]
	v_pk_mul_f32 v[72:73], v[72:73], v[148:149]
	v_pk_mul_f32 v[74:75], v[74:75], v[150:151]
	v_add_u32_e32 v168, 0x42000, v152
	v_pk_mul_f32 v[76:77], v[76:77], v[68:69]
	v_pk_mul_f32 v[78:79], v[78:79], v[70:71]
	v_pk_mul_f32 v[72:73], v[72:73], v[64:65]
	v_pk_mul_f32 v[74:75], v[74:75], v[66:67]
	v_lshl_add_u64 v[154:155], v[168:169], 1, s[64:65]
	v_cvt_pk_bf16_f32 v64, v76, v77
	v_cvt_pk_bf16_f32 v65, v78, v79
	v_cvt_pk_bf16_f32 v66, v72, v73
	v_cvt_pk_bf16_f32 v67, v74, v75
	global_store_dwordx4 v[154:155], v[64:67], off
	v_pk_mul_f32 v[144:145], v[60:61], s[100:101] op_sel_hi:[1,0]
	v_pk_mul_f32 v[146:147], v[62:63], s[100:101] op_sel_hi:[1,0]
	v_pk_mul_f32 v[148:149], v[56:57], s[100:101] op_sel_hi:[1,0]
	v_pk_mul_f32 v[150:151], v[58:59], s[100:101] op_sel_hi:[1,0]
	v_exp_f32_e32 v144, v144
	v_exp_f32_e32 v145, v145
	v_exp_f32_e32 v146, v146
	v_exp_f32_e32 v147, v147
	v_exp_f32_e32 v148, v148
	v_exp_f32_e32 v149, v149
	v_exp_f32_e32 v150, v150
	v_exp_f32_e32 v151, v151
	v_pk_add_f32 v[144:145], v[144:145], 1.0 op_sel_hi:[1,0]
	v_pk_add_f32 v[146:147], v[146:147], 1.0 op_sel_hi:[1,0]
	v_pk_add_f32 v[148:149], v[148:149], 1.0 op_sel_hi:[1,0]
	v_pk_add_f32 v[150:151], v[150:151], 1.0 op_sel_hi:[1,0]
	v_rcp_f32_e32 v144, v144
	v_rcp_f32_e32 v145, v145
	v_rcp_f32_e32 v146, v146
	v_rcp_f32_e32 v147, v147
	v_rcp_f32_e32 v148, v148
	v_rcp_f32_e32 v149, v149
	v_rcp_f32_e32 v150, v150
	v_rcp_f32_e32 v151, v151
	v_pk_mul_f32 v[60:61], v[60:61], v[144:145]
	v_pk_mul_f32 v[62:63], v[62:63], v[146:147]
	v_pk_mul_f32 v[56:57], v[56:57], v[148:149]
	v_pk_mul_f32 v[58:59], v[58:59], v[150:151]
	v_add_u32_e32 v168, 0xb0000, v152
	v_pk_mul_f32 v[60:61], v[60:61], v[52:53]
	v_pk_mul_f32 v[62:63], v[62:63], v[54:55]
	v_pk_mul_f32 v[56:57], v[56:57], v[48:49]
	v_pk_mul_f32 v[58:59], v[58:59], v[50:51]
	v_lshl_add_u64 v[154:155], v[168:169], 1, s[64:65]
	v_cvt_pk_bf16_f32 v48, v60, v61
	v_cvt_pk_bf16_f32 v49, v62, v63
	v_cvt_pk_bf16_f32 v50, v56, v57
	v_cvt_pk_bf16_f32 v51, v58, v59
	global_store_dwordx4 v[154:155], v[48:51], off
	v_pk_mul_f32 v[144:145], v[44:45], s[100:101] op_sel_hi:[1,0]
	v_pk_mul_f32 v[146:147], v[46:47], s[100:101] op_sel_hi:[1,0]
	v_pk_mul_f32 v[148:149], v[40:41], s[100:101] op_sel_hi:[1,0]
	v_pk_mul_f32 v[150:151], v[42:43], s[100:101] op_sel_hi:[1,0]
	v_exp_f32_e32 v144, v144
	v_exp_f32_e32 v145, v145
	v_exp_f32_e32 v146, v146
	v_exp_f32_e32 v147, v147
	v_exp_f32_e32 v148, v148
	v_exp_f32_e32 v149, v149
	v_exp_f32_e32 v150, v150
	v_exp_f32_e32 v151, v151
	v_pk_add_f32 v[144:145], v[144:145], 1.0 op_sel_hi:[1,0]
	v_pk_add_f32 v[146:147], v[146:147], 1.0 op_sel_hi:[1,0]
	v_pk_add_f32 v[148:149], v[148:149], 1.0 op_sel_hi:[1,0]
	v_pk_add_f32 v[150:151], v[150:151], 1.0 op_sel_hi:[1,0]
	v_rcp_f32_e32 v144, v144
	v_rcp_f32_e32 v145, v145
	v_rcp_f32_e32 v146, v146
	v_rcp_f32_e32 v147, v147
	v_rcp_f32_e32 v148, v148
	v_rcp_f32_e32 v149, v149
	v_rcp_f32_e32 v150, v150
	v_rcp_f32_e32 v151, v151
	v_pk_mul_f32 v[44:45], v[44:45], v[144:145]
	v_pk_mul_f32 v[46:47], v[46:47], v[146:147]
	v_pk_mul_f32 v[40:41], v[40:41], v[148:149]
	v_pk_mul_f32 v[42:43], v[42:43], v[150:151]
	v_add_u32_e32 v168, 0xc6000, v152
	v_pk_mul_f32 v[44:45], v[44:45], v[36:37]
	v_pk_mul_f32 v[46:47], v[46:47], v[38:39]
	v_pk_mul_f32 v[40:41], v[40:41], v[32:33]
	v_pk_mul_f32 v[42:43], v[42:43], v[34:35]
	v_lshl_add_u64 v[154:155], v[168:169], 1, s[64:65]
	v_cvt_pk_bf16_f32 v32, v44, v45
	v_cvt_pk_bf16_f32 v33, v46, v47
	v_cvt_pk_bf16_f32 v34, v40, v41
	v_cvt_pk_bf16_f32 v35, v42, v43
	global_store_dwordx4 v[154:155], v[32:35], off
	v_pk_mul_f32 v[144:145], v[28:29], s[100:101] op_sel_hi:[1,0]
	v_pk_mul_f32 v[146:147], v[30:31], s[100:101] op_sel_hi:[1,0]
	v_pk_mul_f32 v[148:149], v[24:25], s[100:101] op_sel_hi:[1,0]
	v_pk_mul_f32 v[150:151], v[26:27], s[100:101] op_sel_hi:[1,0]
	v_exp_f32_e32 v144, v144
	v_exp_f32_e32 v145, v145
	v_exp_f32_e32 v146, v146
	v_exp_f32_e32 v147, v147
	v_exp_f32_e32 v148, v148
	v_exp_f32_e32 v149, v149
	v_exp_f32_e32 v150, v150
	v_exp_f32_e32 v151, v151
	v_pk_add_f32 v[144:145], v[144:145], 1.0 op_sel_hi:[1,0]
	v_pk_add_f32 v[146:147], v[146:147], 1.0 op_sel_hi:[1,0]
	v_pk_add_f32 v[148:149], v[148:149], 1.0 op_sel_hi:[1,0]
	v_pk_add_f32 v[150:151], v[150:151], 1.0 op_sel_hi:[1,0]
	v_rcp_f32_e32 v144, v144
	v_rcp_f32_e32 v145, v145
	v_rcp_f32_e32 v146, v146
	v_rcp_f32_e32 v147, v147
	v_rcp_f32_e32 v148, v148
	v_rcp_f32_e32 v149, v149
	v_rcp_f32_e32 v150, v150
	v_rcp_f32_e32 v151, v151
	v_pk_mul_f32 v[28:29], v[28:29], v[144:145]
	v_pk_mul_f32 v[30:31], v[30:31], v[146:147]
	v_pk_mul_f32 v[24:25], v[24:25], v[148:149]
	v_pk_mul_f32 v[26:27], v[26:27], v[150:151]
	v_add_u32_e32 v168, 0xdc000, v152
	v_pk_mul_f32 v[28:29], v[28:29], v[20:21]
	v_pk_mul_f32 v[30:31], v[30:31], v[22:23]
	v_pk_mul_f32 v[24:25], v[24:25], v[16:17]
	v_pk_mul_f32 v[26:27], v[26:27], v[18:19]
	v_lshl_add_u64 v[154:155], v[168:169], 1, s[64:65]
	v_cvt_pk_bf16_f32 v16, v28, v29
	v_cvt_pk_bf16_f32 v17, v30, v31
	v_cvt_pk_bf16_f32 v18, v24, v25
	v_cvt_pk_bf16_f32 v19, v26, v27
	global_store_dwordx4 v[154:155], v[16:19], off
	v_pk_mul_f32 v[144:145], v[12:13], s[100:101] op_sel_hi:[1,0]
	v_pk_mul_f32 v[146:147], v[14:15], s[100:101] op_sel_hi:[1,0]
	v_pk_mul_f32 v[148:149], v[8:9], s[100:101] op_sel_hi:[1,0]
	v_pk_mul_f32 v[150:151], v[10:11], s[100:101] op_sel_hi:[1,0]
	v_exp_f32_e32 v144, v144
	v_exp_f32_e32 v145, v145
	v_exp_f32_e32 v146, v146
	v_exp_f32_e32 v147, v147
	v_exp_f32_e32 v148, v148
	v_exp_f32_e32 v149, v149
	v_exp_f32_e32 v150, v150
	v_exp_f32_e32 v151, v151
	v_pk_add_f32 v[144:145], v[144:145], 1.0 op_sel_hi:[1,0]
	v_pk_add_f32 v[146:147], v[146:147], 1.0 op_sel_hi:[1,0]
	v_pk_add_f32 v[148:149], v[148:149], 1.0 op_sel_hi:[1,0]
	v_pk_add_f32 v[150:151], v[150:151], 1.0 op_sel_hi:[1,0]
	v_rcp_f32_e32 v144, v144
	v_rcp_f32_e32 v145, v145
	v_rcp_f32_e32 v146, v146
	v_rcp_f32_e32 v147, v147
	v_rcp_f32_e32 v148, v148
	v_rcp_f32_e32 v149, v149
	v_rcp_f32_e32 v150, v150
	v_rcp_f32_e32 v151, v151
	v_pk_mul_f32 v[12:13], v[12:13], v[144:145]
	v_pk_mul_f32 v[14:15], v[14:15], v[146:147]
	v_pk_mul_f32 v[8:9], v[8:9], v[148:149]
	v_pk_mul_f32 v[10:11], v[10:11], v[150:151]
	v_add_u32_e32 v168, 0xf2000, v152
	v_pk_mul_f32 v[12:13], v[12:13], v[4:5]
	v_pk_mul_f32 v[14:15], v[14:15], v[6:7]
	v_pk_mul_f32 v[8:9], v[8:9], v[0:1]
	v_pk_mul_f32 v[10:11], v[10:11], v[2:3]
	v_lshl_add_u64 v[154:155], v[168:169], 1, s[64:65]
	v_cvt_pk_bf16_f32 v0, v12, v13
	v_cvt_pk_bf16_f32 v1, v14, v15
	v_cvt_pk_bf16_f32 v2, v8, v9
	v_cvt_pk_bf16_f32 v3, v10, v11
	global_store_dwordx4 v[154:155], v[0:3], off
	s_cbranch_vccnz .LBB0_226
	s_andn2_b64 vcc, exec, s[6:7]
	s_cbranch_vccnz .LBB0_225
	s_barrier
	s_branch .LBB0_225

; __device__ __forceinline__ v4u pk8(f32x4 a, f32x4 b) { v4u w; w.x = pk2(a[0], a[1]); w.y = pk2(a[2], a[3]); w.z = pk2(b[0], b[1]); w.w = pk2(b[2], b[3]); return w; }
;     __device__ __forceinline__ void operator()(const accv (&acc)[2][2][4][2], const pg8::Unit& u, int wr, int wc, int fr, int fq) const {
;         const int row0 = u.pm * 256 + wr * 64 + fr, col0 = u.pn * 128 + wc * 32 + 8 * fq;
; #pragma unroll
;         for (int ai = 0; ai < 2; ++ai)
; #pragma unroll
;             for (int m = 0; m < 4; ++m) {
;                 f32x4 a[2];
; #pragma unroll
;                 for (int n = 0; n < 2; ++n)
; #pragma unroll
;                     for (int i = 0; i < 4; ++i) { const float g = acc[ai][0][m][n][i], up = acc[ai][1][m][n][i];
;                         a[n][i] = g * __builtin_amdgcn_rcpf(1.f + __builtin_amdgcn_exp2f(-1.4426950408889634f * g)) * up; }
;                 *(v4u*)(O + (unsigned)((row0 + ai * 128 + m * 16) * FF + col0)) = pk8(a[0], a[1]);
;             }
;     }
.LBB0_986:
	v_lshl_add_u32 v147, s68, 8, v140
	v_lshl_or_b32 v146, s14, 7, v142
	s_movk_i32 s2, 0x1600
	s_andn2_b64 vcc, exec, s[0:1]
	s_mov_b64 s[0:1], -1
	s_mov_b32 s100, 0xbfb8aa3b
	s_mov_b32 s101, 0xbfb8aa3b
	v_mad_u64_u32 v[152:153], s[2:3], v147, s2, v[146:147]
	v_pk_mul_f32 v[144:145], v[124:125], s[100:101] op_sel_hi:[1,0]
	v_pk_mul_f32 v[146:147], v[126:127], s[100:101] op_sel_hi:[1,0]
	v_pk_mul_f32 v[148:149], v[120:121], s[100:101] op_sel_hi:[1,0]
	v_pk_mul_f32 v[150:151], v[122:123], s[100:101] op_sel_hi:[1,0]
	v_exp_f32_e32 v144, v144
	v_exp_f32_e32 v145, v145
	v_exp_f32_e32 v146, v146
	v_exp_f32_e32 v147, v147
	v_exp_f32_e32 v148, v148
	v_exp_f32_e32 v149, v149
	v_exp_f32_e32 v150, v150
	v_exp_f32_e32 v151, v151
	v_pk_add_f32 v[144:145], v[144:145], 1.0 op_sel_hi:[1,0]
	v_pk_add_f32 v[146:147], v[146:147], 1.0 op_sel_hi:[1,0]
	v_pk_add_f32 v[148:149], v[148:149], 1.0 op_sel_hi:[1,0]
	v_pk_add_f32 v[150:151], v[150:151], 1.0 op_sel_hi:[1,0]
	v_rcp_f32_e32 v144, v144
	v_rcp_f32_e32 v145, v145
	v_rcp_f32_e32 v146, v146
	v_rcp_f32_e32 v147, v147
	v_rcp_f32_e32 v148, v148
	v_rcp_f32_e32 v149, v149
	v_rcp_f32_e32 v150, v150
	v_rcp_f32_e32 v151, v151
	v_pk_mul_f32 v[124:125], v[124:125], v[144:145]
	v_pk_mul_f32 v[126:127], v[126:127], v[146:147]
	v_pk_mul_f32 v[120:121], v[120:121], v[148:149]
	v_pk_mul_f32 v[122:123], v[122:123], v[150:151]
	v_mov_b32_e32 v168, v152
	v_pk_mul_f32 v[124:125], v[124:125], v[116:117]
	v_pk_mul_f32 v[126:127], v[126:127], v[118:119]
	v_pk_mul_f32 v[120:121], v[120:121], v[112:113]
	v_pk_mul_f32 v[122:123], v[122:123], v[114:115]
	v_lshl_add_u64 v[154:155], v[168:169], 1, s[64:65]
	v_cvt_pk_bf16_f32 v112, v124, v125
	v_cvt_pk_bf16_f32 v113, v126, v127
	v_cvt_pk_bf16_f32 v114, v120, v121
	v_cvt_pk_bf16_f32 v115, v122, v123
	global_store_dwordx4 v[154:155], v[112:115], off
	v_pk_mul_f32 v[144:145], v[108:109], s[100:101] op_sel_hi:[1,0]
	v_pk_mul_f32 v[146:147], v[110:111], s[100:101] op_sel_hi:[1,0]
	v_pk_mul_f32 v[148:149], v[104:105], s[100:101] op_sel_hi:[1,0]
	v_pk_mul_f32 v[150:151], v[106:107], s[100:101] op_sel_hi:[1,0]
	v_exp_f32_e32 v144, v144
	v_exp_f32_e32 v145, v145
	v_exp_f32_e32 v146, v146
	v_exp_f32_e32 v147, v147
	v_exp_f32_e32 v148, v148
	v_exp_f32_e32 v149, v149
	v_exp_f32_e32 v150, v150
	v_exp_f32_e32 v151, v151
	v_pk_add_f32 v[144:145], v[144:145], 1.0 op_sel_hi:[1,0]
	v_pk_add_f32 v[146:147], v[146:147], 1.0 op_sel_hi:[1,0]
	v_pk_add_f32 v[148:149], v[148:149], 1.0 op_sel_hi:[1,0]
	v_pk_add_f32 v[150:151], v[150:151], 1.0 op_sel_hi:[1,0]
	v_rcp_f32_e32 v144, v144
	v_rcp_f32_e32 v145, v145
	v_rcp_f32_e32 v146, v146
	v_rcp_f32_e32 v147, v147
	v_rcp_f32_e32 v148, v148
	v_rcp_f32_e32 v149, v149
	v_rcp_f32_e32 v150, v150
	v_rcp_f32_e32 v151, v151
	v_pk_mul_f32 v[108:109], v[108:109], v[144:145]
	v_pk_mul_f32 v[110:111], v[110:111], v[146:147]
	v_pk_mul_f32 v[104:105], v[104:105], v[148:149]
	v_pk_mul_f32 v[106:107], v[106:107], v[150:151]
	v_add_u32_e32 v168, 0x16000, v152
	v_pk_mul_f32 v[108:109], v[108:109], v[100:101]
	v_pk_mul_f32 v[110:111], v[110:111], v[102:103]
	v_pk_mul_f32 v[104:105], v[104:105], v[96:97]
	v_pk_mul_f32 v[106:107], v[106:107], v[98:99]
	v_lshl_add_u64 v[154:155], v[168:169], 1, s[64:65]
	v_cvt_pk_bf16_f32 v96, v108, v109
	v_cvt_pk_bf16_f32 v97, v110, v111
	v_cvt_pk_bf16_f32 v98, v104, v105
	v_cvt_pk_bf16_f32 v99, v106, v107
	global_store_dwordx4 v[154:155], v[96:99], off
	v_pk_mul_f32 v[144:145], v[92:93], s[100:101] op_sel_hi:[1,0]
	v_pk_mul_f32 v[146:147], v[94:95], s[100:101] op_sel_hi:[1,0]
	v_pk_mul_f32 v[148:149], v[88:89], s[100:101] op_sel_hi:[1,0]
	v_pk_mul_f32 v[150:151], v[90:91], s[100:101] op_sel_hi:[1,0]
	v_exp_f32_e32 v144, v144
	v_exp_f32_e32 v145, v145
	v_exp_f32_e32 v146, v146
	v_exp_f32_e32 v147, v147
	v_exp_f32_e32 v148, v148
	v_exp_f32_e32 v149, v149
	v_exp_f32_e32 v150, v150
	v_exp_f32_e32 v151, v151
	v_pk_add_f32 v[144:145], v[144:145], 1.0 op_sel_hi:[1,0]
	v_pk_add_f32 v[146:147], v[146:147], 1.0 op_sel_hi:[1,0]
	v_pk_add_f32 v[148:149], v[148:149], 1.0 op_sel_hi:[1,0]
	v_pk_add_f32 v[150:151], v[150:151], 1.0 op_sel_hi:[1,0]
	v_rcp_f32_e32 v144, v144
	v_rcp_f32_e32 v145, v145
	v_rcp_f32_e32 v146, v146
	v_rcp_f32_e32 v147, v147
	v_rcp_f32_e32 v148, v148
	v_rcp_f32_e32 v149, v149
	v_rcp_f32_e32 v150, v150
	v_rcp_f32_e32 v151, v151
	v_pk_mul_f32 v[92:93], v[92:93], v[144:145]
	v_pk_mul_f32 v[94:95], v[94:95], v[146:147]
	v_pk_mul_f32 v[88:89], v[88:89], v[148:149]
	v_pk_mul_f32 v[90:91], v[90:91], v[150:151]
	v_add_u32_e32 v168, 0x2c000, v152
	v_pk_mul_f32 v[92:93], v[92:93], v[84:85]
	v_pk_mul_f32 v[94:95], v[94:95], v[86:87]
	v_pk_mul_f32 v[88:89], v[88:89], v[80:81]
	v_pk_mul_f32 v[90:91], v[90:91], v[82:83]
	v_lshl_add_u64 v[154:155], v[168:169], 1, s[64:65]
	v_cvt_pk_bf16_f32 v80, v92, v93
	v_cvt_pk_bf16_f32 v81, v94, v95
	v_cvt_pk_bf16_f32 v82, v88, v89
	v_cvt_pk_bf16_f32 v83, v90, v91
	global_store_dwordx4 v[154:155], v[80:83], off
	v_pk_mul_f32 v[144:145], v[76:77], s[100:101] op_sel_hi:[1,0]
	v_pk_mul_f32 v[146:147], v[78:79], s[100:101] op_sel_hi:[1,0]
	v_pk_mul_f32 v[148:149], v[72:73], s[100:101] op_sel_hi:[1,0]
	v_pk_mul_f32 v[150:151], v[74:75], s[100:101] op_sel_hi:[1,0]
	v_exp_f32_e32 v144, v144
	v_exp_f32_e32 v145, v145
	v_exp_f32_e32 v146, v146
	v_exp_f32_e32 v147, v147
	v_exp_f32_e32 v148, v148
	v_exp_f32_e32 v149, v149
	v_exp_f32_e32 v150, v150
	v_exp_f32_e32 v151, v151
	v_pk_add_f32 v[144:145], v[144:145], 1.0 op_sel_hi:[1,0]
	v_pk_add_f32 v[146:147], v[146:147], 1.0 op_sel_hi:[1,0]
	v_pk_add_f32 v[148:149], v[148:149], 1.0 op_sel_hi:[1,0]
	v_pk_add_f32 v[150:151], v[150:151], 1.0 op_sel_hi:[1,0]
	v_rcp_f32_e32 v144, v144
; __device__ __forceinline__ v4u pk8(f32x4 a, f32x4 b) { v4u w; w.x = pk2(a[0], a[1]); w.y = pk2(a[2], a[3]); w.z = pk2(b[0], b[1]); w.w = pk2(b[2], b[3]); return w; }
;     __device__ __forceinline__ void operator()(const accv (&acc)[2][2][4][2], const pg8::Unit& u, int wr, int wc, int fr, int fq) const {
;         const int row0 = u.pm * 256 + wr * 64 + fr, col0 = u.pn * 128 + wc * 32 + 8 * fq;
; #pragma unroll
;         for (int ai = 0; ai < 2; ++ai)
; #pragma unroll
;             for (int m = 0; m < 4; ++m) {
;                 f32x4 a[2];
; #pragma unroll
;                 for (int n = 0; n < 2; ++n)
; #pragma unroll
;                     for (int i = 0; i < 4; ++i) { const float g = acc[ai][0][m][n][i], up = acc[ai][1][m][n][i];
;                         a[n][i] = g * __builtin_amdgcn_rcpf(1.f + __builtin_amdgcn_exp2f(-1.4426950408889634f * g)) * up; }
;                 *(v4u*)(O + (unsigned)((row0 + ai * 128 + m * 16) * FF + col0)) = pk8(a[0], a[1]);
;             }
	v_rcp_f32_e32 v145, v145
	v_rcp_f32_e32 v146, v146
	v_rcp_f32_e32 v147, v147
	v_rcp_f32_e32 v148, v148
	v_rcp_f32_e32 v149, v149
	v_rcp_f32_e32 v150, v150
	v_rcp_f32_e32 v151, v151
	v_pk_mul_f32 v[76:77], v[76:77], v[144:145]
	v_pk_mul_f32 v[78:79], v[78:79], v[146:147]
	v_pk_mul_f32 v[72:73], v[72:73], v[148:149]
	v_pk_mul_f32 v[74:75], v[74:75], v[150:151]
	v_add_u32_e32 v168, 0x42000, v152
	v_pk_mul_f32 v[76:77], v[76:77], v[68:69]
	v_pk_mul_f32 v[78:79], v[78:79], v[70:71]
	v_pk_mul_f32 v[72:73], v[72:73], v[64:65]
	v_pk_mul_f32 v[74:75], v[74:75], v[66:67]
	v_lshl_add_u64 v[154:155], v[168:169], 1, s[64:65]
	v_cvt_pk_bf16_f32 v64, v76, v77
	v_cvt_pk_bf16_f32 v65, v78, v79
	v_cvt_pk_bf16_f32 v66, v72, v73
	v_cvt_pk_bf16_f32 v67, v74, v75
	global_store_dwordx4 v[154:155], v[64:67], off
	v_pk_mul_f32 v[144:145], v[60:61], s[100:101] op_sel_hi:[1,0]
	v_pk_mul_f32 v[146:147], v[62:63], s[100:101] op_sel_hi:[1,0]
	v_pk_mul_f32 v[148:149], v[56:57], s[100:101] op_sel_hi:[1,0]
	v_pk_mul_f32 v[150:151], v[58:59], s[100:101] op_sel_hi:[1,0]
	v_exp_f32_e32 v144, v144
	v_exp_f32_e32 v145, v145
	v_exp_f32_e32 v146, v146
	v_exp_f32_e32 v147, v147
	v_exp_f32_e32 v148, v148
	v_exp_f32_e32 v149, v149
	v_exp_f32_e32 v150, v150
	v_exp_f32_e32 v151, v151
	v_pk_add_f32 v[144:145], v[144:145], 1.0 op_sel_hi:[1,0]
	v_pk_add_f32 v[146:147], v[146:147], 1.0 op_sel_hi:[1,0]
	v_pk_add_f32 v[148:149], v[148:149], 1.0 op_sel_hi:[1,0]
	v_pk_add_f32 v[150:151], v[150:151], 1.0 op_sel_hi:[1,0]
	v_rcp_f32_e32 v144, v144
	v_rcp_f32_e32 v145, v145
	v_rcp_f32_e32 v146, v146
	v_rcp_f32_e32 v147, v147
	v_rcp_f32_e32 v148, v148
	v_rcp_f32_e32 v149, v149
	v_rcp_f32_e32 v150, v150
	v_rcp_f32_e32 v151, v151
	v_pk_mul_f32 v[60:61], v[60:61], v[144:145]
	v_pk_mul_f32 v[62:63], v[62:63], v[146:147]
	v_pk_mul_f32 v[56:57], v[56:57], v[148:149]
	v_pk_mul_f32 v[58:59], v[58:59], v[150:151]
	v_add_u32_e32 v168, 0xb0000, v152
	v_pk_mul_f32 v[60:61], v[60:61], v[52:53]
	v_pk_mul_f32 v[62:63], v[62:63], v[54:55]
	v_pk_mul_f32 v[56:57], v[56:57], v[48:49]
	v_pk_mul_f32 v[58:59], v[58:59], v[50:51]
	v_lshl_add_u64 v[154:155], v[168:169], 1, s[64:65]
	v_cvt_pk_bf16_f32 v48, v60, v61
	v_cvt_pk_bf16_f32 v49, v62, v63
	v_cvt_pk_bf16_f32 v50, v56, v57
	v_cvt_pk_bf16_f32 v51, v58, v59
	global_store_dwordx4 v[154:155], v[48:51], off
	v_pk_mul_f32 v[144:145], v[44:45], s[100:101] op_sel_hi:[1,0]
	v_pk_mul_f32 v[146:147], v[46:47], s[100:101] op_sel_hi:[1,0]
	v_pk_mul_f32 v[148:149], v[40:41], s[100:101] op_sel_hi:[1,0]
	v_pk_mul_f32 v[150:151], v[42:43], s[100:101] op_sel_hi:[1,0]
	v_exp_f32_e32 v144, v144
	v_exp_f32_e32 v145, v145
	v_exp_f32_e32 v146, v146
	v_exp_f32_e32 v147, v147
	v_exp_f32_e32 v148, v148
	v_exp_f32_e32 v149, v149
	v_exp_f32_e32 v150, v150
	v_exp_f32_e32 v151, v151
	v_pk_add_f32 v[144:145], v[144:145], 1.0 op_sel_hi:[1,0]
	v_pk_add_f32 v[146:147], v[146:147], 1.0 op_sel_hi:[1,0]
	v_pk_add_f32 v[148:149], v[148:149], 1.0 op_sel_hi:[1,0]
	v_pk_add_f32 v[150:151], v[150:151], 1.0 op_sel_hi:[1,0]
	v_rcp_f32_e32 v144, v144
	v_rcp_f32_e32 v145, v145
	v_rcp_f32_e32 v146, v146
	v_rcp_f32_e32 v147, v147
	v_rcp_f32_e32 v148, v148
	v_rcp_f32_e32 v149, v149
	v_rcp_f32_e32 v150, v150
	v_rcp_f32_e32 v151, v151
	v_pk_mul_f32 v[44:45], v[44:45], v[144:145]
	v_pk_mul_f32 v[46:47], v[46:47], v[146:147]
	v_pk_mul_f32 v[40:41], v[40:41], v[148:149]
	v_pk_mul_f32 v[42:43], v[42:43], v[150:151]
	v_add_u32_e32 v168, 0xc6000, v152
	v_pk_mul_f32 v[44:45], v[44:45], v[36:37]
	v_pk_mul_f32 v[46:47], v[46:47], v[38:39]
	v_pk_mul_f32 v[40:41], v[40:41], v[32:33]
	v_pk_mul_f32 v[42:43], v[42:43], v[34:35]
	v_lshl_add_u64 v[154:155], v[168:169], 1, s[64:65]
	v_cvt_pk_bf16_f32 v32, v44, v45
	v_cvt_pk_bf16_f32 v33, v46, v47
	v_cvt_pk_bf16_f32 v34, v40, v41
	v_cvt_pk_bf16_f32 v35, v42, v43
	global_store_dwordx4 v[154:155], v[32:35], off
	v_pk_mul_f32 v[144:145], v[28:29], s[100:101] op_sel_hi:[1,0]
	v_pk_mul_f32 v[146:147], v[30:31], s[100:101] op_sel_hi:[1,0]
	v_pk_mul_f32 v[148:149], v[24:25], s[100:101] op_sel_hi:[1,0]
	v_pk_mul_f32 v[150:151], v[26:27], s[100:101] op_sel_hi:[1,0]
	v_exp_f32_e32 v144, v144
	v_exp_f32_e32 v145, v145
	v_exp_f32_e32 v146, v146
	v_exp_f32_e32 v147, v147
	v_exp_f32_e32 v148, v148
	v_exp_f32_e32 v149, v149
	v_exp_f32_e32 v150, v150
	v_exp_f32_e32 v151, v151
	v_pk_add_f32 v[144:145], v[144:145], 1.0 op_sel_hi:[1,0]
	v_pk_add_f32 v[146:147], v[146:147], 1.0 op_sel_hi:[1,0]
	v_pk_add_f32 v[148:149], v[148:149], 1.0 op_sel_hi:[1,0]
	v_pk_add_f32 v[150:151], v[150:151], 1.0 op_sel_hi:[1,0]
	v_rcp_f32_e32 v144, v144
	v_rcp_f32_e32 v145, v145
	v_rcp_f32_e32 v146, v146
	v_rcp_f32_e32 v147, v147
	v_rcp_f32_e32 v148, v148
	v_rcp_f32_e32 v149, v149
	v_rcp_f32_e32 v150, v150
	v_rcp_f32_e32 v151, v151
	v_pk_mul_f32 v[28:29], v[28:29], v[144:145]
	v_pk_mul_f32 v[30:31], v[30:31], v[146:147]
	v_pk_mul_f32 v[24:25], v[24:25], v[148:149]
	v_pk_mul_f32 v[26:27], v[26:27], v[150:151]
	v_add_u32_e32 v168, 0xdc000, v152
	v_pk_mul_f32 v[28:29], v[28:29], v[20:21]
	v_pk_mul_f32 v[30:31], v[30:31], v[22:23]
	v_pk_mul_f32 v[24:25], v[24:25], v[16:17]
	v_pk_mul_f32 v[26:27], v[26:27], v[18:19]
	v_lshl_add_u64 v[154:155], v[168:169], 1, s[64:65]
	v_cvt_pk_bf16_f32 v16, v28, v29
	v_cvt_pk_bf16_f32 v17, v30, v31
	v_cvt_pk_bf16_f32 v18, v24, v25
	v_cvt_pk_bf16_f32 v19, v26, v27
	global_store_dwordx4 v[154:155], v[16:19], off
	v_pk_mul_f32 v[144:145], v[12:13], s[100:101] op_sel_hi:[1,0]
	v_pk_mul_f32 v[146:147], v[14:15], s[100:101] op_sel_hi:[1,0]
	v_pk_mul_f32 v[148:149], v[8:9], s[100:101] op_sel_hi:[1,0]
	v_pk_mul_f32 v[150:151], v[10:11], s[100:101] op_sel_hi:[1,0]
	v_exp_f32_e32 v144, v144
	v_exp_f32_e32 v145, v145
	v_exp_f32_e32 v146, v146
	v_exp_f32_e32 v147, v147
	v_exp_f32_e32 v148, v148
	v_exp_f32_e32 v149, v149
	v_exp_f32_e32 v150, v150
	v_exp_f32_e32 v151, v151
	v_pk_add_f32 v[144:145], v[144:145], 1.0 op_sel_hi:[1,0]
	v_pk_add_f32 v[146:147], v[146:147], 1.0 op_sel_hi:[1,0]
	v_pk_add_f32 v[148:149], v[148:149], 1.0 op_sel_hi:[1,0]
	v_pk_add_f32 v[150:151], v[150:151], 1.0 op_sel_hi:[1,0]
	v_rcp_f32_e32 v144, v144
	v_rcp_f32_e32 v145, v145
	v_rcp_f32_e32 v146, v146
	v_rcp_f32_e32 v147, v147
	v_rcp_f32_e32 v148, v148
	v_rcp_f32_e32 v149, v149
	v_rcp_f32_e32 v150, v150
	v_rcp_f32_e32 v151, v151
	v_pk_mul_f32 v[12:13], v[12:13], v[144:145]
	v_pk_mul_f32 v[14:15], v[14:15], v[146:147]
	v_pk_mul_f32 v[8:9], v[8:9], v[148:149]
	v_pk_mul_f32 v[10:11], v[10:11], v[150:151]
	v_add_u32_e32 v168, 0xf2000, v152
	v_pk_mul_f32 v[12:13], v[12:13], v[4:5]
	v_pk_mul_f32 v[14:15], v[14:15], v[6:7]
	v_pk_mul_f32 v[8:9], v[8:9], v[0:1]
	v_pk_mul_f32 v[10:11], v[10:11], v[2:3]
	v_lshl_add_u64 v[154:155], v[168:169], 1, s[64:65]
	v_cvt_pk_bf16_f32 v0, v12, v13
	v_cvt_pk_bf16_f32 v1, v14, v15
	v_cvt_pk_bf16_f32 v2, v8, v9
	v_cvt_pk_bf16_f32 v3, v10, v11
	global_store_dwordx4 v[154:155], v[0:3], off
	s_cbranch_vccnz .LBB0_979
	s_andn2_b64 vcc, exec, s[4:5]
	s_cbranch_vccnz .LBB0_978
	s_barrier
	s_branch .LBB0_978
